# SwiGLU epilogue: rs^2 folded into the denominator with v_pk_fma_f32 (4 packed multiplies fewer per row group), on top of the fused-exp attention
# baseline (speedup 1.0000x reference)
; __device__ __forceinline__ unsigned cvt_pk_bf16(float lo, float hi) { unsigned r; asm volatile("v_cvt_pk_bf16_f32 %0, %1, %2" : "=v"(r) : "v"(lo), "v"(hi)); return r; }
;     __device__ __forceinline__ void operator()(const f32x4 (&acc)[2][2][4][2], const Unit& u, int wr, int wc, int fr, int fq) const {
;     ...
;         for (int ai = 0; ai < 2; ++ai)
; #pragma unroll
;             for (int m = 0; m < 4; ++m) rsv[ai][m] = rsT[u.ui * 256 + ai * HALF + wr * 64 + m * 16 + fr];
; #pragma unroll
;         for (int ai = 0; ai < 2; ++ai)
; #pragma unroll
;             for (int m = 0; m < 4; ++m) {
;                 bf16_t* rowp = O + (size_t)(row0 + ai * HALF + m * 16) * FF + col0;
;                 const float rs = rsv[ai][m];
;                 float a[8];
; #pragma unroll
;                 for (int n = 0; n < 2; ++n)
; #pragma unroll
;                     for (int j = 0; j < 4; ++j) { const float g = acc[ai][0][m][n][j] * rs, up = acc[ai][1][m][n][j] * rs;
;                         const float sg = g * __builtin_amdgcn_rcpf(1.0f + __builtin_amdgcn_exp2f(-1.4426950408889634f * g)); a[n * 4 + j] = sg * up; }
;                 u32x4 w; w.x = cvt_pk_bf16(a[0], a[1]); w.y = cvt_pk_bf16(a[2], a[3]); w.z = cvt_pk_bf16(a[4], a[5]); w.w = cvt_pk_bf16(a[6], a[7]);
;                 *(u32x4*)rowp = w;
.LBB0_2281:
	v_lshl_add_u32 v140, s68, 10, v154
	ds_read2_b32 v[148:149], v140 offset1:16
	ds_read2_b32 v[146:147], v140 offset0:32 offset1:48
	ds_read2_b32 v[144:145], v140 offset0:128 offset1:144
	ds_read2_b32 v[140:141], v140 offset0:160 offset1:176
	v_lshl_or_b32 v150, s17, 7, v155
	v_lshl_add_u32 v157, s16, 8, v152
	v_ashrrev_i32_e32 v151, 31, v150
	v_mov_b64_e32 v[142:143], s[84:85]
	s_andn2_b64 vcc, exec, s[2:3]
	v_lshlrev_b64 v[150:151], 1, v[150:151]
	v_mov_b32_e32 v176, 1.0
	v_mov_b32_e32 v177, 0xbfb8aa3b
	v_lshl_add_u64 v[142:143], v[142:143], 0, v[150:151]
	s_waitcnt lgkmcnt(0)
	v_pk_mul_f32 v[178:179], v[148:149], v[176:177] op_sel:[0,1] op_sel_hi:[1,1]
	v_pk_mul_f32 v[180:181], v[146:147], v[176:177] op_sel:[0,1] op_sel_hi:[1,1]
	v_pk_mul_f32 v[182:183], v[144:145], v[176:177] op_sel:[0,1] op_sel_hi:[1,1]
	v_pk_mul_f32 v[184:185], v[140:141], v[176:177] op_sel:[0,1] op_sel_hi:[1,1]
	v_pk_mul_f32 v[186:187], v[148:149], v[148:149]
	v_pk_mul_f32 v[188:189], v[146:147], v[146:147]
	v_pk_mul_f32 v[190:191], v[144:145], v[144:145]
	v_pk_mul_f32 v[192:193], v[140:141], v[140:141]
	v_rcp_f32_e32 v186, v186
	v_rcp_f32_e32 v187, v187
	v_rcp_f32_e32 v188, v188
	v_rcp_f32_e32 v189, v189
	v_rcp_f32_e32 v190, v190
	v_rcp_f32_e32 v191, v191
	v_rcp_f32_e32 v192, v192
	v_rcp_f32_e32 v193, v193
	s_nop 0
	v_mad_i64_i32 v[194:195], s[16:17], v157, s81, v[142:143]
	v_pk_mul_f32 v[122:123], v[126:127], v[122:123]
	v_pk_mul_f32 v[124:125], v[128:129], v[124:125]
	v_pk_mul_f32 v[114:115], v[118:119], v[114:115]
	v_pk_mul_f32 v[116:117], v[120:121], v[116:117]
	v_pk_mul_f32 v[126:127], v[126:127], v[178:179] op_sel_hi:[1,0]
	v_pk_mul_f32 v[128:129], v[128:129], v[178:179] op_sel_hi:[1,0]
	v_pk_mul_f32 v[118:119], v[118:119], v[178:179] op_sel_hi:[1,0]
	v_pk_mul_f32 v[120:121], v[120:121], v[178:179] op_sel_hi:[1,0]
	v_exp_f32_e32 v126, v126
	v_exp_f32_e32 v127, v127
	v_exp_f32_e32 v128, v128
	v_exp_f32_e32 v129, v129
	v_exp_f32_e32 v118, v118
	v_exp_f32_e32 v119, v119
	v_exp_f32_e32 v120, v120
	v_exp_f32_e32 v121, v121
	v_pk_fma_f32 v[126:127], v[126:127], v[186:187], v[186:187] op_sel_hi:[1,0,0]
	v_pk_fma_f32 v[128:129], v[128:129], v[186:187], v[186:187] op_sel_hi:[1,0,0]
	v_pk_fma_f32 v[118:119], v[118:119], v[186:187], v[186:187] op_sel_hi:[1,0,0]
	v_pk_fma_f32 v[120:121], v[120:121], v[186:187], v[186:187] op_sel_hi:[1,0,0]
	v_rcp_f32_e32 v126, v126
	v_rcp_f32_e32 v127, v127
	v_rcp_f32_e32 v128, v128
	v_rcp_f32_e32 v129, v129
	v_rcp_f32_e32 v118, v118
	v_rcp_f32_e32 v119, v119
	v_rcp_f32_e32 v120, v120
	v_rcp_f32_e32 v121, v121
	v_pk_mul_f32 v[122:123], v[122:123], v[126:127]
	v_pk_mul_f32 v[124:125], v[124:125], v[128:129]
	v_pk_mul_f32 v[114:115], v[114:115], v[118:119]
	v_pk_mul_f32 v[116:117], v[116:117], v[120:121]
	v_cvt_pk_bf16_f32 v126, v122, v123
	v_cvt_pk_bf16_f32 v127, v124, v125
	v_cvt_pk_bf16_f32 v128, v114, v115
	v_cvt_pk_bf16_f32 v129, v116, v117
	global_store_dwordx4 v[194:195], v[126:129], off
	v_add_u32_e32 v196, 0x10, v157
	v_mad_i64_i32 v[196:197], s[16:17], v196, s81, v[142:143]
	v_pk_mul_f32 v[106:107], v[110:111], v[106:107]
	v_pk_mul_f32 v[108:109], v[112:113], v[108:109]
	v_pk_mul_f32 v[98:99], v[102:103], v[98:99]
	v_pk_mul_f32 v[100:101], v[104:105], v[100:101]
	v_pk_mul_f32 v[110:111], v[110:111], v[178:179] op_sel:[0,1] op_sel_hi:[1,1]
	v_pk_mul_f32 v[112:113], v[112:113], v[178:179] op_sel:[0,1] op_sel_hi:[1,1]
	v_pk_mul_f32 v[102:103], v[102:103], v[178:179] op_sel:[0,1] op_sel_hi:[1,1]
	v_pk_mul_f32 v[104:105], v[104:105], v[178:179] op_sel:[0,1] op_sel_hi:[1,1]
	v_exp_f32_e32 v110, v110
	v_exp_f32_e32 v111, v111
	v_exp_f32_e32 v112, v112
	v_exp_f32_e32 v113, v113
	v_exp_f32_e32 v102, v102
	v_exp_f32_e32 v103, v103
	v_exp_f32_e32 v104, v104
	v_exp_f32_e32 v105, v105
	v_pk_fma_f32 v[110:111], v[110:111], v[186:187], v[186:187] op_sel:[0,1,1] op_sel_hi:[1,1,1]
	v_pk_fma_f32 v[112:113], v[112:113], v[186:187], v[186:187] op_sel:[0,1,1] op_sel_hi:[1,1,1]
	v_pk_fma_f32 v[102:103], v[102:103], v[186:187], v[186:187] op_sel:[0,1,1] op_sel_hi:[1,1,1]
	v_pk_fma_f32 v[104:105], v[104:105], v[186:187], v[186:187] op_sel:[0,1,1] op_sel_hi:[1,1,1]
	v_rcp_f32_e32 v110, v110
	v_rcp_f32_e32 v111, v111
	v_rcp_f32_e32 v112, v112
	v_rcp_f32_e32 v113, v113
	v_rcp_f32_e32 v102, v102
	v_rcp_f32_e32 v103, v103
	v_rcp_f32_e32 v104, v104
	v_rcp_f32_e32 v105, v105
	v_pk_mul_f32 v[106:107], v[106:107], v[110:111]
	v_pk_mul_f32 v[108:109], v[108:109], v[112:113]
	v_pk_mul_f32 v[98:99], v[98:99], v[102:103]
	v_pk_mul_f32 v[100:101], v[100:101], v[104:105]
	v_cvt_pk_bf16_f32 v110, v106, v107
	v_cvt_pk_bf16_f32 v111, v108, v109
	v_cvt_pk_bf16_f32 v112, v98, v99
	v_cvt_pk_bf16_f32 v113, v100, v101
	global_store_dwordx4 v[196:197], v[110:113], off
	v_add_u32_e32 v194, 0x20, v157
	v_mad_i64_i32 v[194:195], s[16:17], v194, s81, v[142:143]
	v_pk_mul_f32 v[90:91], v[94:95], v[90:91]
	v_pk_mul_f32 v[92:93], v[96:97], v[92:93]
	v_pk_mul_f32 v[82:83], v[86:87], v[82:83]
	v_pk_mul_f32 v[84:85], v[88:89], v[84:85]
	v_pk_mul_f32 v[94:95], v[94:95], v[180:181] op_sel_hi:[1,0]
	v_pk_mul_f32 v[96:97], v[96:97], v[180:181] op_sel_hi:[1,0]
	v_pk_mul_f32 v[86:87], v[86:87], v[180:181] op_sel_hi:[1,0]
	v_pk_mul_f32 v[88:89], v[88:89], v[180:181] op_sel_hi:[1,0]
	v_exp_f32_e32 v94, v94
	v_exp_f32_e32 v95, v95
	v_exp_f32_e32 v96, v96
	v_exp_f32_e32 v97, v97
	v_exp_f32_e32 v86, v86
	v_exp_f32_e32 v87, v87
	v_exp_f32_e32 v88, v88
	v_exp_f32_e32 v89, v89
	v_pk_fma_f32 v[94:95], v[94:95], v[188:189], v[188:189] op_sel_hi:[1,0,0]
	v_pk_fma_f32 v[96:97], v[96:97], v[188:189], v[188:189] op_sel_hi:[1,0,0]
	v_pk_fma_f32 v[86:87], v[86:87], v[188:189], v[188:189] op_sel_hi:[1,0,0]
; __device__ __forceinline__ unsigned cvt_pk_bf16(float lo, float hi) { unsigned r; asm volatile("v_cvt_pk_bf16_f32 %0, %1, %2" : "=v"(r) : "v"(lo), "v"(hi)); return r; }
;     __device__ __forceinline__ void operator()(const f32x4 (&acc)[2][2][4][2], const Unit& u, int wr, int wc, int fr, int fq) const {
;     ...
;         for (int ai = 0; ai < 2; ++ai)
; #pragma unroll
;             for (int m = 0; m < 4; ++m) {
;                 bf16_t* rowp = O + (size_t)(row0 + ai * HALF + m * 16) * FF + col0;
;                 const float rs = rsv[ai][m];
;                 float a[8];
; #pragma unroll
;                 for (int n = 0; n < 2; ++n)
; #pragma unroll
;                     for (int j = 0; j < 4; ++j) { const float g = acc[ai][0][m][n][j] * rs, up = acc[ai][1][m][n][j] * rs;
;                         const float sg = g * __builtin_amdgcn_rcpf(1.0f + __builtin_amdgcn_exp2f(-1.4426950408889634f * g)); a[n * 4 + j] = sg * up; }
;                 u32x4 w; w.x = cvt_pk_bf16(a[0], a[1]); w.y = cvt_pk_bf16(a[2], a[3]); w.z = cvt_pk_bf16(a[4], a[5]); w.w = cvt_pk_bf16(a[6], a[7]);
;                 *(u32x4*)rowp = w;
	v_pk_fma_f32 v[88:89], v[88:89], v[188:189], v[188:189] op_sel_hi:[1,0,0]
	v_rcp_f32_e32 v94, v94
	v_rcp_f32_e32 v95, v95
	v_rcp_f32_e32 v96, v96
	v_rcp_f32_e32 v97, v97
	v_rcp_f32_e32 v86, v86
	v_rcp_f32_e32 v87, v87
	v_rcp_f32_e32 v88, v88
	v_rcp_f32_e32 v89, v89
	v_pk_mul_f32 v[90:91], v[90:91], v[94:95]
	v_pk_mul_f32 v[92:93], v[92:93], v[96:97]
	v_pk_mul_f32 v[82:83], v[82:83], v[86:87]
	v_pk_mul_f32 v[84:85], v[84:85], v[88:89]
	v_cvt_pk_bf16_f32 v94, v90, v91
	v_cvt_pk_bf16_f32 v95, v92, v93
	v_cvt_pk_bf16_f32 v96, v82, v83
	v_cvt_pk_bf16_f32 v97, v84, v85
	global_store_dwordx4 v[194:195], v[94:97], off
	v_add_u32_e32 v196, 0x30, v157
	v_mad_i64_i32 v[196:197], s[16:17], v196, s81, v[142:143]
	v_pk_mul_f32 v[74:75], v[78:79], v[74:75]
	v_pk_mul_f32 v[76:77], v[80:81], v[76:77]
	v_pk_mul_f32 v[66:67], v[70:71], v[66:67]
	v_pk_mul_f32 v[68:69], v[72:73], v[68:69]
	v_pk_mul_f32 v[78:79], v[78:79], v[180:181] op_sel:[0,1] op_sel_hi:[1,1]
	v_pk_mul_f32 v[80:81], v[80:81], v[180:181] op_sel:[0,1] op_sel_hi:[1,1]
	v_pk_mul_f32 v[70:71], v[70:71], v[180:181] op_sel:[0,1] op_sel_hi:[1,1]
	v_pk_mul_f32 v[72:73], v[72:73], v[180:181] op_sel:[0,1] op_sel_hi:[1,1]
	v_exp_f32_e32 v78, v78
	v_exp_f32_e32 v79, v79
	v_exp_f32_e32 v80, v80
	v_exp_f32_e32 v81, v81
	v_exp_f32_e32 v70, v70
	v_exp_f32_e32 v71, v71
	v_exp_f32_e32 v72, v72
	v_exp_f32_e32 v73, v73
	v_pk_fma_f32 v[78:79], v[78:79], v[188:189], v[188:189] op_sel:[0,1,1] op_sel_hi:[1,1,1]
	v_pk_fma_f32 v[80:81], v[80:81], v[188:189], v[188:189] op_sel:[0,1,1] op_sel_hi:[1,1,1]
	v_pk_fma_f32 v[70:71], v[70:71], v[188:189], v[188:189] op_sel:[0,1,1] op_sel_hi:[1,1,1]
	v_pk_fma_f32 v[72:73], v[72:73], v[188:189], v[188:189] op_sel:[0,1,1] op_sel_hi:[1,1,1]
	v_rcp_f32_e32 v78, v78
	v_rcp_f32_e32 v79, v79
	v_rcp_f32_e32 v80, v80
	v_rcp_f32_e32 v81, v81
	v_rcp_f32_e32 v70, v70
	v_rcp_f32_e32 v71, v71
	v_rcp_f32_e32 v72, v72
	v_rcp_f32_e32 v73, v73
	v_pk_mul_f32 v[74:75], v[74:75], v[78:79]
	v_pk_mul_f32 v[76:77], v[76:77], v[80:81]
	v_pk_mul_f32 v[66:67], v[66:67], v[70:71]
	v_pk_mul_f32 v[68:69], v[68:69], v[72:73]
	v_cvt_pk_bf16_f32 v78, v74, v75
	v_cvt_pk_bf16_f32 v79, v76, v77
	v_cvt_pk_bf16_f32 v80, v66, v67
	v_cvt_pk_bf16_f32 v81, v68, v69
	global_store_dwordx4 v[196:197], v[78:81], off
	v_add_u32_e32 v194, 0x80, v157
	v_mad_i64_i32 v[194:195], s[16:17], v194, s81, v[142:143]
	v_pk_mul_f32 v[58:59], v[62:63], v[58:59]
	v_pk_mul_f32 v[60:61], v[64:65], v[60:61]
	v_pk_mul_f32 v[50:51], v[54:55], v[50:51]
	v_pk_mul_f32 v[52:53], v[56:57], v[52:53]
	v_pk_mul_f32 v[62:63], v[62:63], v[182:183] op_sel_hi:[1,0]
	v_pk_mul_f32 v[64:65], v[64:65], v[182:183] op_sel_hi:[1,0]
	v_pk_mul_f32 v[54:55], v[54:55], v[182:183] op_sel_hi:[1,0]
	v_pk_mul_f32 v[56:57], v[56:57], v[182:183] op_sel_hi:[1,0]
	v_exp_f32_e32 v62, v62
	v_exp_f32_e32 v63, v63
	v_exp_f32_e32 v64, v64
	v_exp_f32_e32 v65, v65
	v_exp_f32_e32 v54, v54
	v_exp_f32_e32 v55, v55
	v_exp_f32_e32 v56, v56
	v_exp_f32_e32 v57, v57
	v_pk_fma_f32 v[62:63], v[62:63], v[190:191], v[190:191] op_sel_hi:[1,0,0]
	v_pk_fma_f32 v[64:65], v[64:65], v[190:191], v[190:191] op_sel_hi:[1,0,0]
	v_pk_fma_f32 v[54:55], v[54:55], v[190:191], v[190:191] op_sel_hi:[1,0,0]
	v_pk_fma_f32 v[56:57], v[56:57], v[190:191], v[190:191] op_sel_hi:[1,0,0]
	v_rcp_f32_e32 v62, v62
	v_rcp_f32_e32 v63, v63
	v_rcp_f32_e32 v64, v64
	v_rcp_f32_e32 v65, v65
	v_rcp_f32_e32 v54, v54
	v_rcp_f32_e32 v55, v55
	v_rcp_f32_e32 v56, v56
	v_rcp_f32_e32 v57, v57
	v_pk_mul_f32 v[58:59], v[58:59], v[62:63]
	v_pk_mul_f32 v[60:61], v[60:61], v[64:65]
	v_pk_mul_f32 v[50:51], v[50:51], v[54:55]
	v_pk_mul_f32 v[52:53], v[52:53], v[56:57]
	v_cvt_pk_bf16_f32 v62, v58, v59
	v_cvt_pk_bf16_f32 v63, v60, v61
	v_cvt_pk_bf16_f32 v64, v50, v51
	v_cvt_pk_bf16_f32 v65, v52, v53
	global_store_dwordx4 v[194:195], v[62:65], off
	v_add_u32_e32 v196, 0x90, v157
	v_mad_i64_i32 v[196:197], s[16:17], v196, s81, v[142:143]
	v_pk_mul_f32 v[42:43], v[46:47], v[42:43]
	v_pk_mul_f32 v[44:45], v[48:49], v[44:45]
	v_pk_mul_f32 v[34:35], v[38:39], v[34:35]
	v_pk_mul_f32 v[36:37], v[40:41], v[36:37]
	v_pk_mul_f32 v[46:47], v[46:47], v[182:183] op_sel:[0,1] op_sel_hi:[1,1]
	v_pk_mul_f32 v[48:49], v[48:49], v[182:183] op_sel:[0,1] op_sel_hi:[1,1]
	v_pk_mul_f32 v[38:39], v[38:39], v[182:183] op_sel:[0,1] op_sel_hi:[1,1]
	v_pk_mul_f32 v[40:41], v[40:41], v[182:183] op_sel:[0,1] op_sel_hi:[1,1]
; __device__ __forceinline__ unsigned cvt_pk_bf16(float lo, float hi) { unsigned r; asm volatile("v_cvt_pk_bf16_f32 %0, %1, %2" : "=v"(r) : "v"(lo), "v"(hi)); return r; }
;     __device__ __forceinline__ void operator()(const f32x4 (&acc)[2][2][4][2], const Unit& u, int wr, int wc, int fr, int fq) const {
;     ...
;         for (int ai = 0; ai < 2; ++ai)
; #pragma unroll
;             for (int m = 0; m < 4; ++m) {
;                 bf16_t* rowp = O + (size_t)(row0 + ai * HALF + m * 16) * FF + col0;
;                 const float rs = rsv[ai][m];
;                 float a[8];
; #pragma unroll
;                 for (int n = 0; n < 2; ++n)
; #pragma unroll
;                     for (int j = 0; j < 4; ++j) { const float g = acc[ai][0][m][n][j] * rs, up = acc[ai][1][m][n][j] * rs;
;                         const float sg = g * __builtin_amdgcn_rcpf(1.0f + __builtin_amdgcn_exp2f(-1.4426950408889634f * g)); a[n * 4 + j] = sg * up; }
;                 u32x4 w; w.x = cvt_pk_bf16(a[0], a[1]); w.y = cvt_pk_bf16(a[2], a[3]); w.z = cvt_pk_bf16(a[4], a[5]); w.w = cvt_pk_bf16(a[6], a[7]);
;                 *(u32x4*)rowp = w;
	v_exp_f32_e32 v46, v46
	v_exp_f32_e32 v47, v47
	v_exp_f32_e32 v48, v48
	v_exp_f32_e32 v49, v49
	v_exp_f32_e32 v38, v38
	v_exp_f32_e32 v39, v39
	v_exp_f32_e32 v40, v40
	v_exp_f32_e32 v41, v41
	v_pk_fma_f32 v[46:47], v[46:47], v[190:191], v[190:191] op_sel:[0,1,1] op_sel_hi:[1,1,1]
	v_pk_fma_f32 v[48:49], v[48:49], v[190:191], v[190:191] op_sel:[0,1,1] op_sel_hi:[1,1,1]
	v_pk_fma_f32 v[38:39], v[38:39], v[190:191], v[190:191] op_sel:[0,1,1] op_sel_hi:[1,1,1]
	v_pk_fma_f32 v[40:41], v[40:41], v[190:191], v[190:191] op_sel:[0,1,1] op_sel_hi:[1,1,1]
	v_rcp_f32_e32 v46, v46
	v_rcp_f32_e32 v47, v47
	v_rcp_f32_e32 v48, v48
	v_rcp_f32_e32 v49, v49
	v_rcp_f32_e32 v38, v38
	v_rcp_f32_e32 v39, v39
	v_rcp_f32_e32 v40, v40
	v_rcp_f32_e32 v41, v41
	v_pk_mul_f32 v[42:43], v[42:43], v[46:47]
	v_pk_mul_f32 v[44:45], v[44:45], v[48:49]
	v_pk_mul_f32 v[34:35], v[34:35], v[38:39]
	v_pk_mul_f32 v[36:37], v[36:37], v[40:41]
	v_cvt_pk_bf16_f32 v46, v42, v43
	v_cvt_pk_bf16_f32 v47, v44, v45
	v_cvt_pk_bf16_f32 v48, v34, v35
	v_cvt_pk_bf16_f32 v49, v36, v37
	global_store_dwordx4 v[196:197], v[46:49], off
	v_add_u32_e32 v194, 0xa0, v157
	v_mad_i64_i32 v[194:195], s[16:17], v194, s81, v[142:143]
	v_pk_mul_f32 v[26:27], v[30:31], v[26:27]
	v_pk_mul_f32 v[28:29], v[32:33], v[28:29]
	v_pk_mul_f32 v[18:19], v[22:23], v[18:19]
	v_pk_mul_f32 v[20:21], v[24:25], v[20:21]
	v_pk_mul_f32 v[30:31], v[30:31], v[184:185] op_sel_hi:[1,0]
	v_pk_mul_f32 v[32:33], v[32:33], v[184:185] op_sel_hi:[1,0]
	v_pk_mul_f32 v[22:23], v[22:23], v[184:185] op_sel_hi:[1,0]
	v_pk_mul_f32 v[24:25], v[24:25], v[184:185] op_sel_hi:[1,0]
	v_exp_f32_e32 v30, v30
	v_exp_f32_e32 v31, v31
	v_exp_f32_e32 v32, v32
	v_exp_f32_e32 v33, v33
	v_exp_f32_e32 v22, v22
	v_exp_f32_e32 v23, v23
	v_exp_f32_e32 v24, v24
	v_exp_f32_e32 v25, v25
	v_pk_fma_f32 v[30:31], v[30:31], v[192:193], v[192:193] op_sel_hi:[1,0,0]
	v_pk_fma_f32 v[32:33], v[32:33], v[192:193], v[192:193] op_sel_hi:[1,0,0]
	v_pk_fma_f32 v[22:23], v[22:23], v[192:193], v[192:193] op_sel_hi:[1,0,0]
	v_pk_fma_f32 v[24:25], v[24:25], v[192:193], v[192:193] op_sel_hi:[1,0,0]
	v_rcp_f32_e32 v30, v30
	v_rcp_f32_e32 v31, v31
	v_rcp_f32_e32 v32, v32
	v_rcp_f32_e32 v33, v33
	v_rcp_f32_e32 v22, v22
	v_rcp_f32_e32 v23, v23
	v_rcp_f32_e32 v24, v24
	v_rcp_f32_e32 v25, v25
	v_pk_mul_f32 v[26:27], v[26:27], v[30:31]
	v_pk_mul_f32 v[28:29], v[28:29], v[32:33]
	v_pk_mul_f32 v[18:19], v[18:19], v[22:23]
	v_pk_mul_f32 v[20:21], v[20:21], v[24:25]
	v_cvt_pk_bf16_f32 v30, v26, v27
	v_cvt_pk_bf16_f32 v31, v28, v29
	v_cvt_pk_bf16_f32 v32, v18, v19
	v_cvt_pk_bf16_f32 v33, v20, v21
	global_store_dwordx4 v[194:195], v[30:33], off
	v_add_u32_e32 v196, 0xb0, v157
	v_mad_i64_i32 v[196:197], s[16:17], v196, s81, v[142:143]
	v_pk_mul_f32 v[10:11], v[14:15], v[10:11]
	v_pk_mul_f32 v[12:13], v[16:17], v[12:13]
	v_pk_mul_f32 v[2:3], v[6:7], v[2:3]
	v_pk_mul_f32 v[4:5], v[8:9], v[4:5]
	v_pk_mul_f32 v[14:15], v[14:15], v[184:185] op_sel:[0,1] op_sel_hi:[1,1]
	v_pk_mul_f32 v[16:17], v[16:17], v[184:185] op_sel:[0,1] op_sel_hi:[1,1]
	v_pk_mul_f32 v[6:7], v[6:7], v[184:185] op_sel:[0,1] op_sel_hi:[1,1]
	v_pk_mul_f32 v[8:9], v[8:9], v[184:185] op_sel:[0,1] op_sel_hi:[1,1]
	v_exp_f32_e32 v14, v14
	v_exp_f32_e32 v15, v15
	v_exp_f32_e32 v16, v16
	v_exp_f32_e32 v17, v17
	v_exp_f32_e32 v6, v6
	v_exp_f32_e32 v7, v7
	v_exp_f32_e32 v8, v8
	v_exp_f32_e32 v9, v9
	v_pk_fma_f32 v[14:15], v[14:15], v[192:193], v[192:193] op_sel:[0,1,1] op_sel_hi:[1,1,1]
	v_pk_fma_f32 v[16:17], v[16:17], v[192:193], v[192:193] op_sel:[0,1,1] op_sel_hi:[1,1,1]
	v_pk_fma_f32 v[6:7], v[6:7], v[192:193], v[192:193] op_sel:[0,1,1] op_sel_hi:[1,1,1]
	v_pk_fma_f32 v[8:9], v[8:9], v[192:193], v[192:193] op_sel:[0,1,1] op_sel_hi:[1,1,1]
	v_rcp_f32_e32 v14, v14
	v_rcp_f32_e32 v15, v15
	v_rcp_f32_e32 v16, v16
	v_rcp_f32_e32 v17, v17
	v_rcp_f32_e32 v6, v6
	v_rcp_f32_e32 v7, v7
	v_rcp_f32_e32 v8, v8
	v_rcp_f32_e32 v9, v9
	v_pk_mul_f32 v[10:11], v[10:11], v[14:15]
	v_pk_mul_f32 v[12:13], v[12:13], v[16:17]
	v_pk_mul_f32 v[2:3], v[2:3], v[6:7]
	v_pk_mul_f32 v[4:5], v[4:5], v[8:9]
	v_cvt_pk_bf16_f32 v14, v10, v11
	v_cvt_pk_bf16_f32 v15, v12, v13
	v_cvt_pk_bf16_f32 v16, v2, v3
	v_cvt_pk_bf16_f32 v17, v4, v5
	global_store_dwordx4 v[196:197], v[14:17], off
	s_mov_b64 s[16:17], -1
	s_cbranch_vccnz .LBB0_2270
	s_andn2_b64 vcc, exec, s[4:5]
	s_cbranch_vccnz .LBB0_2269
	s_barrier
	s_branch .LBB0_2269
